# producer priority 3 and all 16 LDS-DMA pieces of a K-tile issued right after the stage-free barrier
# baseline (speedup 1.0000x reference)
.Lpc_prod_5:
	s_setprio 3

.Lpc_pgo_5:
	s_nop 0
	s_sub_u32 s26, s26, s98
	s_subb_u32 s27, s27, 0
	s_sub_u32 s38, s38, s99
	s_subb_u32 s39, s39, 0
	s_mov_b32 vcc_hi, vcc_lo
	s_add_u32 m0, s30, -1
	s_and_b32 vcc_hi, vcc_hi, m0
	s_lshl_b32 vcc_hi, vcc_hi, 7
	v_add_u32_e32 v20, vcc_hi, v4
	v_add_u32_e32 v21, vcc_hi, v5
	v_add_u32_e32 v22, vcc_hi, v6
	v_add_u32_e32 v23, vcc_hi, v7
	v_add_u32_e32 v24, vcc_hi, v8
	v_add_u32_e32 v25, vcc_hi, v9
	v_add_u32_e32 v26, vcc_hi, v10
	v_add_u32_e32 v27, vcc_hi, v11
	v_add_u32_e32 v28, vcc_hi, v12
	v_add_u32_e32 v29, vcc_hi, v13
	v_add_u32_e32 v30, vcc_hi, v14
	v_add_u32_e32 v31, vcc_hi, v15
	v_add_u32_e32 v32, vcc_hi, v16
	v_add_u32_e32 v33, vcc_hi, v17
	v_add_u32_e32 v34, vcc_hi, v18
	v_add_u32_e32 v35, vcc_hi, v19
	s_add_u32 vcc_lo, vcc_lo, 1
	s_barrier
	s_add_u32 m0, s100, 0x0
	s_nop 0
	global_load_lds_dwordx4 v20, s[26:27]
	s_add_u32 m0, s100, 0x400
	s_nop 0
	global_load_lds_dwordx4 v21, s[26:27]
	s_add_u32 m0, s100, 0x1000
	s_nop 0
	global_load_lds_dwordx4 v22, s[26:27]
	s_add_u32 m0, s100, 0x1400
	s_nop 0
	global_load_lds_dwordx4 v23, s[26:27]
	s_add_u32 m0, s100, 0x2000
	s_nop 0
	global_load_lds_dwordx4 v24, s[26:27]
	s_add_u32 m0, s100, 0x2400
	s_nop 0
	global_load_lds_dwordx4 v25, s[26:27]
	s_add_u32 m0, s100, 0x3000
	s_nop 0
	global_load_lds_dwordx4 v26, s[26:27]
	s_add_u32 m0, s100, 0x3400
	s_nop 0
	global_load_lds_dwordx4 v27, s[26:27]
	s_add_u32 m0, s100, 0x4000
	s_nop 0
	global_load_lds_dwordx4 v28, s[38:39]
	s_add_u32 m0, s100, 0x4400
	s_nop 0
	global_load_lds_dwordx4 v29, s[38:39]
	s_add_u32 m0, s100, 0x5000
	s_nop 0
	global_load_lds_dwordx4 v30, s[38:39]
	s_add_u32 m0, s100, 0x5400
	s_nop 0
	global_load_lds_dwordx4 v31, s[38:39]
	s_add_u32 m0, s100, 0x6000
	s_nop 0
	global_load_lds_dwordx4 v32, s[38:39]
	s_add_u32 m0, s100, 0x6400
	s_nop 0
	global_load_lds_dwordx4 v33, s[38:39]
	s_add_u32 m0, s100, 0x7000
	s_nop 0
	global_load_lds_dwordx4 v34, s[38:39]
	s_add_u32 m0, s100, 0x7400
	s_nop 0
	global_load_lds_dwordx4 v35, s[38:39]
	s_waitcnt vmcnt(16)
	s_barrier
	s_mov_b32 vcc_hi, vcc_lo
	s_add_u32 m0, s30, -1
	s_and_b32 vcc_hi, vcc_hi, m0
	s_lshl_b32 vcc_hi, vcc_hi, 7
	v_add_u32_e32 v20, vcc_hi, v4
	v_add_u32_e32 v21, vcc_hi, v5
	v_add_u32_e32 v22, vcc_hi, v6
	v_add_u32_e32 v23, vcc_hi, v7
	v_add_u32_e32 v24, vcc_hi, v8
	v_add_u32_e32 v25, vcc_hi, v9
	v_add_u32_e32 v26, vcc_hi, v10
	v_add_u32_e32 v27, vcc_hi, v11
	v_add_u32_e32 v28, vcc_hi, v12
	v_add_u32_e32 v29, vcc_hi, v13
	v_add_u32_e32 v30, vcc_hi, v14
	v_add_u32_e32 v31, vcc_hi, v15
	v_add_u32_e32 v32, vcc_hi, v16
	v_add_u32_e32 v33, vcc_hi, v17
	v_add_u32_e32 v34, vcc_hi, v18
	v_add_u32_e32 v35, vcc_hi, v19
	s_add_u32 vcc_lo, vcc_lo, 1
	s_barrier
	s_add_u32 m0, s100, 0x8000
	s_nop 0
	global_load_lds_dwordx4 v20, s[26:27]
	s_add_u32 m0, s100, 0x8400
	s_nop 0
	global_load_lds_dwordx4 v21, s[26:27]
	s_add_u32 m0, s100, 0x9000
	s_nop 0
	global_load_lds_dwordx4 v22, s[26:27]
	s_add_u32 m0, s100, 0x9400
	s_nop 0
	global_load_lds_dwordx4 v23, s[26:27]
	s_add_u32 m0, s100, 0xa000
	s_nop 0
	global_load_lds_dwordx4 v24, s[26:27]
	s_add_u32 m0, s100, 0xa400
	s_nop 0
	global_load_lds_dwordx4 v25, s[26:27]
	s_add_u32 m0, s100, 0xb000
	s_nop 0
	global_load_lds_dwordx4 v26, s[26:27]
	s_add_u32 m0, s100, 0xb400
	s_nop 0
	global_load_lds_dwordx4 v27, s[26:27]
	s_add_u32 m0, s100, 0xc000
	s_nop 0
	global_load_lds_dwordx4 v28, s[38:39]
	s_add_u32 m0, s100, 0xc400
	s_nop 0
	global_load_lds_dwordx4 v29, s[38:39]
	s_add_u32 m0, s100, 0xd000
	s_nop 0
	global_load_lds_dwordx4 v30, s[38:39]
	s_add_u32 m0, s100, 0xd400
	s_nop 0
	global_load_lds_dwordx4 v31, s[38:39]
	s_add_u32 m0, s100, 0xe000
	s_nop 0
	global_load_lds_dwordx4 v32, s[38:39]
	s_add_u32 m0, s100, 0xe400
	s_nop 0
	global_load_lds_dwordx4 v33, s[38:39]
	s_add_u32 m0, s100, 0xf000
	s_nop 0
	global_load_lds_dwordx4 v34, s[38:39]
	s_add_u32 m0, s100, 0xf400
	s_nop 0
	global_load_lds_dwordx4 v35, s[38:39]
	s_waitcnt vmcnt(16)
	s_barrier
	s_add_u32 s24, s24, 0x100
	s_addc_u32 s25, s25, 0
	s_add_i32 s53, s53, 2
	s_cmp_le_i32 s53, s52
	s_cbranch_scc1 .Lpc_ptop_5
	s_setprio 0
	s_add_i32 s42, s42, 1
	s_mov_b32 s46, s44
	s_mov_b32 s47, s45
	s_cmp_eq_u32 s42, 3
	s_cbranch_scc0 .Lpc_pnd_5
	s_waitcnt vmcnt(0)
	s_branch .LBB0_165

.Lpc_pgo_2:
	s_nop 0
	s_sub_u32 s40, s40, s98
	s_subb_u32 s41, s41, 0
	s_sub_u32 s38, s38, s99
	s_subb_u32 s39, s39, 0
	s_bfe_u32 vcc_hi, s101, 0x80008
	s_add_u32 vcc_hi, vcc_hi, vcc_lo
	s_add_u32 m0, s42, -1
	s_and_b32 vcc_hi, vcc_hi, m0
	s_lshl_b32 vcc_hi, vcc_hi, 7
	v_add_u32_e32 v20, vcc_hi, v4
	v_add_u32_e32 v21, vcc_hi, v5
	v_add_u32_e32 v22, vcc_hi, v6
	v_add_u32_e32 v23, vcc_hi, v7
	v_add_u32_e32 v24, vcc_hi, v8
	v_add_u32_e32 v25, vcc_hi, v9
	v_add_u32_e32 v26, vcc_hi, v10
	v_add_u32_e32 v27, vcc_hi, v11
	v_add_u32_e32 v28, vcc_hi, v12
	v_add_u32_e32 v29, vcc_hi, v13
	v_add_u32_e32 v30, vcc_hi, v14
	v_add_u32_e32 v31, vcc_hi, v15
	v_add_u32_e32 v32, vcc_hi, v16
	v_add_u32_e32 v33, vcc_hi, v17
	v_add_u32_e32 v34, vcc_hi, v18
	v_add_u32_e32 v35, vcc_hi, v19
	s_add_u32 vcc_lo, vcc_lo, 1
	s_barrier
	s_add_u32 m0, s100, 0x0
	s_nop 0
	global_load_lds_dwordx4 v20, s[40:41]
	s_add_u32 m0, s100, 0x400
	s_nop 0
	global_load_lds_dwordx4 v21, s[40:41]
	s_add_u32 m0, s100, 0x1000
	s_nop 0
	global_load_lds_dwordx4 v22, s[40:41]
	s_add_u32 m0, s100, 0x1400
	s_nop 0
	global_load_lds_dwordx4 v23, s[40:41]
	s_add_u32 m0, s100, 0x2000
	s_nop 0
	global_load_lds_dwordx4 v24, s[40:41]
	s_add_u32 m0, s100, 0x2400
	s_nop 0
	global_load_lds_dwordx4 v25, s[40:41]
	s_add_u32 m0, s100, 0x3000
	s_nop 0
	global_load_lds_dwordx4 v26, s[40:41]
	s_add_u32 m0, s100, 0x3400
	s_nop 0
	global_load_lds_dwordx4 v27, s[40:41]
	s_add_u32 m0, s100, 0x4000
	s_nop 0
	global_load_lds_dwordx4 v28, s[38:39]
	s_add_u32 m0, s100, 0x4400
	s_nop 0
	global_load_lds_dwordx4 v29, s[38:39]
	s_add_u32 m0, s100, 0x5000
	s_nop 0
	global_load_lds_dwordx4 v30, s[38:39]
	s_add_u32 m0, s100, 0x5400
	s_nop 0
	global_load_lds_dwordx4 v31, s[38:39]
	s_add_u32 m0, s100, 0x6000
	s_nop 0
	global_load_lds_dwordx4 v32, s[38:39]
	s_add_u32 m0, s100, 0x6400
	s_nop 0
	global_load_lds_dwordx4 v33, s[38:39]
	s_add_u32 m0, s100, 0x7000
	s_nop 0
	global_load_lds_dwordx4 v34, s[38:39]
	s_add_u32 m0, s100, 0x7400
	s_nop 0
	global_load_lds_dwordx4 v35, s[38:39]
	s_waitcnt vmcnt(16)
	s_barrier
	s_bfe_u32 vcc_hi, s101, 0x80008
	s_add_u32 vcc_hi, vcc_hi, vcc_lo
	s_add_u32 m0, s42, -1
	s_and_b32 vcc_hi, vcc_hi, m0
	s_lshl_b32 vcc_hi, vcc_hi, 7
	v_add_u32_e32 v20, vcc_hi, v4
	v_add_u32_e32 v21, vcc_hi, v5
	v_add_u32_e32 v22, vcc_hi, v6
	v_add_u32_e32 v23, vcc_hi, v7
	v_add_u32_e32 v24, vcc_hi, v8
	v_add_u32_e32 v25, vcc_hi, v9
	v_add_u32_e32 v26, vcc_hi, v10
	v_add_u32_e32 v27, vcc_hi, v11
	v_add_u32_e32 v28, vcc_hi, v12
	v_add_u32_e32 v29, vcc_hi, v13
	v_add_u32_e32 v30, vcc_hi, v14
	v_add_u32_e32 v31, vcc_hi, v15
	v_add_u32_e32 v32, vcc_hi, v16
	v_add_u32_e32 v33, vcc_hi, v17
	v_add_u32_e32 v34, vcc_hi, v18
	v_add_u32_e32 v35, vcc_hi, v19
	s_add_u32 vcc_lo, vcc_lo, 1
	s_barrier
	s_add_u32 m0, s100, 0x8000
	s_nop 0
	global_load_lds_dwordx4 v20, s[40:41]
	s_add_u32 m0, s100, 0x8400
	s_nop 0
	global_load_lds_dwordx4 v21, s[40:41]
	s_add_u32 m0, s100, 0x9000
	s_nop 0
	global_load_lds_dwordx4 v22, s[40:41]
	s_add_u32 m0, s100, 0x9400
	s_nop 0
	global_load_lds_dwordx4 v23, s[40:41]
	s_add_u32 m0, s100, 0xa000
	s_nop 0
	global_load_lds_dwordx4 v24, s[40:41]
	s_add_u32 m0, s100, 0xa400
	s_nop 0
	global_load_lds_dwordx4 v25, s[40:41]
	s_add_u32 m0, s100, 0xb000
	s_nop 0
	global_load_lds_dwordx4 v26, s[40:41]
	s_add_u32 m0, s100, 0xb400
	s_nop 0
	global_load_lds_dwordx4 v27, s[40:41]
	s_add_u32 m0, s100, 0xc000
	s_nop 0
	global_load_lds_dwordx4 v28, s[38:39]
	s_add_u32 m0, s100, 0xc400
	s_nop 0
	global_load_lds_dwordx4 v29, s[38:39]
	s_add_u32 m0, s100, 0xd000
	s_nop 0
	global_load_lds_dwordx4 v30, s[38:39]
	s_add_u32 m0, s100, 0xd400
	s_nop 0
	global_load_lds_dwordx4 v31, s[38:39]
	s_add_u32 m0, s100, 0xe000
	s_nop 0
	global_load_lds_dwordx4 v32, s[38:39]
	s_add_u32 m0, s100, 0xe400
	s_nop 0
	global_load_lds_dwordx4 v33, s[38:39]
	s_add_u32 m0, s100, 0xf000
	s_nop 0
	global_load_lds_dwordx4 v34, s[38:39]
	s_add_u32 m0, s100, 0xf400
	s_nop 0
	global_load_lds_dwordx4 v35, s[38:39]
	s_waitcnt vmcnt(16)
	s_barrier
	s_add_u32 s34, s34, 0x100
	s_addc_u32 s35, s35, 0
	s_add_i32 s55, s55, 2
	s_cmp_le_i32 s55, s47
	s_cbranch_scc1 .Lpc_ptop_2
	s_setprio 0
	s_movk_i32 s55, 0x4000
	s_mov_b32 s53, s1
	s_mov_b32 s52, s3
	s_and_b64 vcc, exec, s[26:27]
	v_mov_b64_e32 v[146:147], v[142:143]
	v_mov_b64_e32 v[144:145], v[140:141]
	s_cbranch_vccz .Lpc_pnd_2
	s_waitcnt vmcnt(0)
	s_branch .LBB0_191

.Lpc_pgo_6:
	s_nop 0
	s_sub_u32 s26, s26, s98
	s_subb_u32 s27, s27, 0
	s_sub_u32 s38, s38, s99
	s_subb_u32 s39, s39, 0
	s_mov_b32 vcc_hi, vcc_lo
	s_add_u32 m0, s30, -1
	s_and_b32 vcc_hi, vcc_hi, m0
	s_lshl_b32 vcc_hi, vcc_hi, 7
	v_add_u32_e32 v20, vcc_hi, v4
	v_add_u32_e32 v21, vcc_hi, v5
	v_add_u32_e32 v22, vcc_hi, v6
	v_add_u32_e32 v23, vcc_hi, v7
	v_add_u32_e32 v24, vcc_hi, v8
	v_add_u32_e32 v25, vcc_hi, v9
	v_add_u32_e32 v26, vcc_hi, v10
	v_add_u32_e32 v27, vcc_hi, v11
	v_add_u32_e32 v28, vcc_hi, v12
	v_add_u32_e32 v29, vcc_hi, v13
	v_add_u32_e32 v30, vcc_hi, v14
	v_add_u32_e32 v31, vcc_hi, v15
	v_add_u32_e32 v32, vcc_hi, v16
	v_add_u32_e32 v33, vcc_hi, v17
	v_add_u32_e32 v34, vcc_hi, v18
	v_add_u32_e32 v35, vcc_hi, v19
	s_add_u32 vcc_lo, vcc_lo, 1
	s_barrier
	s_add_u32 m0, s100, 0x0
	s_nop 0
	global_load_lds_dwordx4 v20, s[26:27]
	s_add_u32 m0, s100, 0x400
	s_nop 0
	global_load_lds_dwordx4 v21, s[26:27]
	s_add_u32 m0, s100, 0x1000
	s_nop 0
	global_load_lds_dwordx4 v22, s[26:27]
	s_add_u32 m0, s100, 0x1400
	s_nop 0
	global_load_lds_dwordx4 v23, s[26:27]
	s_add_u32 m0, s100, 0x2000
	s_nop 0
	global_load_lds_dwordx4 v24, s[26:27]
	s_add_u32 m0, s100, 0x2400
	s_nop 0
	global_load_lds_dwordx4 v25, s[26:27]
	s_add_u32 m0, s100, 0x3000
	s_nop 0
	global_load_lds_dwordx4 v26, s[26:27]
	s_add_u32 m0, s100, 0x3400
	s_nop 0
	global_load_lds_dwordx4 v27, s[26:27]
	s_add_u32 m0, s100, 0x4000
	s_nop 0
	global_load_lds_dwordx4 v28, s[38:39]
	s_add_u32 m0, s100, 0x4400
	s_nop 0
	global_load_lds_dwordx4 v29, s[38:39]
	s_add_u32 m0, s100, 0x5000
	s_nop 0
	global_load_lds_dwordx4 v30, s[38:39]
	s_add_u32 m0, s100, 0x5400
	s_nop 0
	global_load_lds_dwordx4 v31, s[38:39]
	s_add_u32 m0, s100, 0x6000
	s_nop 0
	global_load_lds_dwordx4 v32, s[38:39]
	s_add_u32 m0, s100, 0x6400
	s_nop 0
	global_load_lds_dwordx4 v33, s[38:39]
	s_add_u32 m0, s100, 0x7000
	s_nop 0
	global_load_lds_dwordx4 v34, s[38:39]
	s_add_u32 m0, s100, 0x7400
	s_nop 0
	global_load_lds_dwordx4 v35, s[38:39]
	s_waitcnt vmcnt(16)
	s_barrier
	s_mov_b32 vcc_hi, vcc_lo
	s_add_u32 m0, s30, -1
	s_and_b32 vcc_hi, vcc_hi, m0
	s_lshl_b32 vcc_hi, vcc_hi, 7
	v_add_u32_e32 v20, vcc_hi, v4
	v_add_u32_e32 v21, vcc_hi, v5
	v_add_u32_e32 v22, vcc_hi, v6
	v_add_u32_e32 v23, vcc_hi, v7
	v_add_u32_e32 v24, vcc_hi, v8
	v_add_u32_e32 v25, vcc_hi, v9
	v_add_u32_e32 v26, vcc_hi, v10
	v_add_u32_e32 v27, vcc_hi, v11
	v_add_u32_e32 v28, vcc_hi, v12
	v_add_u32_e32 v29, vcc_hi, v13
	v_add_u32_e32 v30, vcc_hi, v14
	v_add_u32_e32 v31, vcc_hi, v15
	v_add_u32_e32 v32, vcc_hi, v16
	v_add_u32_e32 v33, vcc_hi, v17
	v_add_u32_e32 v34, vcc_hi, v18
	v_add_u32_e32 v35, vcc_hi, v19
	s_add_u32 vcc_lo, vcc_lo, 1
	s_barrier
	s_add_u32 m0, s100, 0x8000
	s_nop 0
	global_load_lds_dwordx4 v20, s[26:27]
	s_add_u32 m0, s100, 0x8400
	s_nop 0
	global_load_lds_dwordx4 v21, s[26:27]
	s_add_u32 m0, s100, 0x9000
	s_nop 0
	global_load_lds_dwordx4 v22, s[26:27]
	s_add_u32 m0, s100, 0x9400
	s_nop 0
	global_load_lds_dwordx4 v23, s[26:27]
	s_add_u32 m0, s100, 0xa000
	s_nop 0
	global_load_lds_dwordx4 v24, s[26:27]
	s_add_u32 m0, s100, 0xa400
	s_nop 0
	global_load_lds_dwordx4 v25, s[26:27]
	s_add_u32 m0, s100, 0xb000
	s_nop 0
	global_load_lds_dwordx4 v26, s[26:27]
	s_add_u32 m0, s100, 0xb400
	s_nop 0
	global_load_lds_dwordx4 v27, s[26:27]
	s_add_u32 m0, s100, 0xc000
	s_nop 0
	global_load_lds_dwordx4 v28, s[38:39]
	s_add_u32 m0, s100, 0xc400
	s_nop 0
	global_load_lds_dwordx4 v29, s[38:39]
	s_add_u32 m0, s100, 0xd000
	s_nop 0
	global_load_lds_dwordx4 v30, s[38:39]
	s_add_u32 m0, s100, 0xd400
	s_nop 0
	global_load_lds_dwordx4 v31, s[38:39]
	s_add_u32 m0, s100, 0xe000
	s_nop 0
	global_load_lds_dwordx4 v32, s[38:39]
	s_add_u32 m0, s100, 0xe400
	s_nop 0
	global_load_lds_dwordx4 v33, s[38:39]
	s_add_u32 m0, s100, 0xf000
	s_nop 0
	global_load_lds_dwordx4 v34, s[38:39]
	s_add_u32 m0, s100, 0xf400
	s_nop 0
	global_load_lds_dwordx4 v35, s[38:39]
	s_waitcnt vmcnt(16)
	s_barrier
	s_add_u32 s24, s24, 0x100
	s_addc_u32 s25, s25, 0
	s_add_i32 s52, s52, 2
	s_cmp_le_i32 s52, s49
	s_cbranch_scc1 .Lpc_ptop_6
	s_setprio 0
	s_add_i32 s42, s42, 1
	s_mov_b32 s46, s44
	s_mov_b32 s47, s45
	s_cmp_eq_u32 s42, 3
	s_cbranch_scc0 .Lpc_pnd_6
	s_waitcnt vmcnt(0)
	s_branch .LBB0_276

.Lpc_pgo_3:
	s_nop 0
	s_sub_u32 s40, s40, s98
	s_subb_u32 s41, s41, 0
	s_sub_u32 s38, s38, s99
	s_subb_u32 s39, s39, 0
	s_bfe_u32 vcc_hi, s101, 0x80008
	s_add_u32 vcc_hi, vcc_hi, vcc_lo
	s_add_u32 m0, s42, -1
	s_and_b32 vcc_hi, vcc_hi, m0
	s_lshl_b32 vcc_hi, vcc_hi, 7
	v_add_u32_e32 v20, vcc_hi, v4
	v_add_u32_e32 v21, vcc_hi, v5
	v_add_u32_e32 v22, vcc_hi, v6
	v_add_u32_e32 v23, vcc_hi, v7
	v_add_u32_e32 v24, vcc_hi, v8
	v_add_u32_e32 v25, vcc_hi, v9
	v_add_u32_e32 v26, vcc_hi, v10
	v_add_u32_e32 v27, vcc_hi, v11
	v_add_u32_e32 v28, vcc_hi, v12
	v_add_u32_e32 v29, vcc_hi, v13
	v_add_u32_e32 v30, vcc_hi, v14
	v_add_u32_e32 v31, vcc_hi, v15
	v_add_u32_e32 v32, vcc_hi, v16
	v_add_u32_e32 v33, vcc_hi, v17
	v_add_u32_e32 v34, vcc_hi, v18
	v_add_u32_e32 v35, vcc_hi, v19
	s_add_u32 vcc_lo, vcc_lo, 1
	s_barrier
	s_add_u32 m0, s100, 0x0
	s_nop 0
	global_load_lds_dwordx4 v20, s[40:41]
	s_add_u32 m0, s100, 0x400
	s_nop 0
	global_load_lds_dwordx4 v21, s[40:41]
	s_add_u32 m0, s100, 0x1000
	s_nop 0
	global_load_lds_dwordx4 v22, s[40:41]
	s_add_u32 m0, s100, 0x1400
	s_nop 0
	global_load_lds_dwordx4 v23, s[40:41]
	s_add_u32 m0, s100, 0x2000
	s_nop 0
	global_load_lds_dwordx4 v24, s[40:41]
	s_add_u32 m0, s100, 0x2400
	s_nop 0
	global_load_lds_dwordx4 v25, s[40:41]
	s_add_u32 m0, s100, 0x3000
	s_nop 0
	global_load_lds_dwordx4 v26, s[40:41]
	s_add_u32 m0, s100, 0x3400
	s_nop 0
	global_load_lds_dwordx4 v27, s[40:41]
	s_add_u32 m0, s100, 0x4000
	s_nop 0
	global_load_lds_dwordx4 v28, s[38:39]
	s_add_u32 m0, s100, 0x4400
	s_nop 0
	global_load_lds_dwordx4 v29, s[38:39]
	s_add_u32 m0, s100, 0x5000
	s_nop 0
	global_load_lds_dwordx4 v30, s[38:39]
	s_add_u32 m0, s100, 0x5400
	s_nop 0
	global_load_lds_dwordx4 v31, s[38:39]
	s_add_u32 m0, s100, 0x6000
	s_nop 0
	global_load_lds_dwordx4 v32, s[38:39]
	s_add_u32 m0, s100, 0x6400
	s_nop 0
	global_load_lds_dwordx4 v33, s[38:39]
	s_add_u32 m0, s100, 0x7000
	s_nop 0
	global_load_lds_dwordx4 v34, s[38:39]
	s_add_u32 m0, s100, 0x7400
	s_nop 0
	global_load_lds_dwordx4 v35, s[38:39]
	s_waitcnt vmcnt(16)
	s_barrier
	s_bfe_u32 vcc_hi, s101, 0x80008
	s_add_u32 vcc_hi, vcc_hi, vcc_lo
	s_add_u32 m0, s42, -1
	s_and_b32 vcc_hi, vcc_hi, m0
	s_lshl_b32 vcc_hi, vcc_hi, 7
	v_add_u32_e32 v20, vcc_hi, v4
	v_add_u32_e32 v21, vcc_hi, v5
	v_add_u32_e32 v22, vcc_hi, v6
	v_add_u32_e32 v23, vcc_hi, v7
	v_add_u32_e32 v24, vcc_hi, v8
	v_add_u32_e32 v25, vcc_hi, v9
	v_add_u32_e32 v26, vcc_hi, v10
	v_add_u32_e32 v27, vcc_hi, v11
	v_add_u32_e32 v28, vcc_hi, v12
	v_add_u32_e32 v29, vcc_hi, v13
	v_add_u32_e32 v30, vcc_hi, v14
	v_add_u32_e32 v31, vcc_hi, v15
	v_add_u32_e32 v32, vcc_hi, v16
	v_add_u32_e32 v33, vcc_hi, v17
	v_add_u32_e32 v34, vcc_hi, v18
	v_add_u32_e32 v35, vcc_hi, v19
	s_add_u32 vcc_lo, vcc_lo, 1
	s_barrier
	s_add_u32 m0, s100, 0x8000
	s_nop 0
	global_load_lds_dwordx4 v20, s[40:41]
	s_add_u32 m0, s100, 0x8400
	s_nop 0
	global_load_lds_dwordx4 v21, s[40:41]
	s_add_u32 m0, s100, 0x9000
	s_nop 0
	global_load_lds_dwordx4 v22, s[40:41]
	s_add_u32 m0, s100, 0x9400
	s_nop 0
	global_load_lds_dwordx4 v23, s[40:41]
	s_add_u32 m0, s100, 0xa000
	s_nop 0
	global_load_lds_dwordx4 v24, s[40:41]
	s_add_u32 m0, s100, 0xa400
	s_nop 0
	global_load_lds_dwordx4 v25, s[40:41]
	s_add_u32 m0, s100, 0xb000
	s_nop 0
	global_load_lds_dwordx4 v26, s[40:41]
	s_add_u32 m0, s100, 0xb400
	s_nop 0
	global_load_lds_dwordx4 v27, s[40:41]
	s_add_u32 m0, s100, 0xc000
	s_nop 0
	global_load_lds_dwordx4 v28, s[38:39]
	s_add_u32 m0, s100, 0xc400
	s_nop 0
	global_load_lds_dwordx4 v29, s[38:39]
	s_add_u32 m0, s100, 0xd000
	s_nop 0
	global_load_lds_dwordx4 v30, s[38:39]
	s_add_u32 m0, s100, 0xd400
	s_nop 0
	global_load_lds_dwordx4 v31, s[38:39]
	s_add_u32 m0, s100, 0xe000
	s_nop 0
	global_load_lds_dwordx4 v32, s[38:39]
	s_add_u32 m0, s100, 0xe400
	s_nop 0
	global_load_lds_dwordx4 v33, s[38:39]
	s_add_u32 m0, s100, 0xf000
	s_nop 0
	global_load_lds_dwordx4 v34, s[38:39]
	s_add_u32 m0, s100, 0xf400
	s_nop 0
	global_load_lds_dwordx4 v35, s[38:39]
	s_waitcnt vmcnt(16)
	s_barrier
	s_add_u32 s34, s34, 0x100
	s_addc_u32 s35, s35, 0
	s_add_i32 s96, s96, 2
	s_cmp_le_i32 s96, s47
	s_cbranch_scc1 .Lpc_ptop_3
	s_setprio 0
	s_mov_b32 s97, s5
	s_movk_i32 s96, 0x43ff
	s_mov_b32 s55, s49
	s_mov_b32 s53, s1
	s_and_b64 vcc, exec, s[26:27]
	v_mov_b64_e32 v[146:147], v[142:143]
	v_mov_b64_e32 v[144:145], v[140:141]
	s_cbranch_vccz .Lpc_pnd_3
	s_waitcnt vmcnt(0)
	s_branch .LBB0_319

.Lpc_pgo_4:
	s_nop 0
	s_sub_u32 s40, s40, s98
	s_subb_u32 s41, s41, 0
	s_sub_u32 s38, s38, s99
	s_subb_u32 s39, s39, 0
	s_bfe_u32 vcc_hi, s101, 0x80008
	s_add_u32 vcc_hi, vcc_hi, vcc_lo
	s_add_u32 m0, s42, -1
	s_and_b32 vcc_hi, vcc_hi, m0
	s_lshl_b32 vcc_hi, vcc_hi, 7
	v_add_u32_e32 v20, vcc_hi, v4
	v_add_u32_e32 v21, vcc_hi, v5
	v_add_u32_e32 v22, vcc_hi, v6
	v_add_u32_e32 v23, vcc_hi, v7
	v_add_u32_e32 v24, vcc_hi, v8
	v_add_u32_e32 v25, vcc_hi, v9
	v_add_u32_e32 v26, vcc_hi, v10
	v_add_u32_e32 v27, vcc_hi, v11
	v_add_u32_e32 v28, vcc_hi, v12
	v_add_u32_e32 v29, vcc_hi, v13
	v_add_u32_e32 v30, vcc_hi, v14
	v_add_u32_e32 v31, vcc_hi, v15
	v_add_u32_e32 v32, vcc_hi, v16
	v_add_u32_e32 v33, vcc_hi, v17
	v_add_u32_e32 v34, vcc_hi, v18
	v_add_u32_e32 v35, vcc_hi, v19
	s_add_u32 vcc_lo, vcc_lo, 1
	s_barrier
	s_add_u32 m0, s100, 0x0
	s_nop 0
	global_load_lds_dwordx4 v20, s[40:41]
	s_add_u32 m0, s100, 0x400
	s_nop 0
	global_load_lds_dwordx4 v21, s[40:41]
	s_add_u32 m0, s100, 0x1000
	s_nop 0
	global_load_lds_dwordx4 v22, s[40:41]
	s_add_u32 m0, s100, 0x1400
	s_nop 0
	global_load_lds_dwordx4 v23, s[40:41]
	s_add_u32 m0, s100, 0x2000
	s_nop 0
	global_load_lds_dwordx4 v24, s[40:41]
	s_add_u32 m0, s100, 0x2400
	s_nop 0
	global_load_lds_dwordx4 v25, s[40:41]
	s_add_u32 m0, s100, 0x3000
	s_nop 0
	global_load_lds_dwordx4 v26, s[40:41]
	s_add_u32 m0, s100, 0x3400
	s_nop 0
	global_load_lds_dwordx4 v27, s[40:41]
	s_add_u32 m0, s100, 0x4000
	s_nop 0
	global_load_lds_dwordx4 v28, s[38:39]
	s_add_u32 m0, s100, 0x4400
	s_nop 0
	global_load_lds_dwordx4 v29, s[38:39]
	s_add_u32 m0, s100, 0x5000
	s_nop 0
	global_load_lds_dwordx4 v30, s[38:39]
	s_add_u32 m0, s100, 0x5400
	s_nop 0
	global_load_lds_dwordx4 v31, s[38:39]
	s_add_u32 m0, s100, 0x6000
	s_nop 0
	global_load_lds_dwordx4 v32, s[38:39]
	s_add_u32 m0, s100, 0x6400
	s_nop 0
	global_load_lds_dwordx4 v33, s[38:39]
	s_add_u32 m0, s100, 0x7000
	s_nop 0
	global_load_lds_dwordx4 v34, s[38:39]
	s_add_u32 m0, s100, 0x7400
	s_nop 0
	global_load_lds_dwordx4 v35, s[38:39]
	s_waitcnt vmcnt(16)
	s_barrier
	s_bfe_u32 vcc_hi, s101, 0x80008
	s_add_u32 vcc_hi, vcc_hi, vcc_lo
	s_add_u32 m0, s42, -1
	s_and_b32 vcc_hi, vcc_hi, m0
	s_lshl_b32 vcc_hi, vcc_hi, 7
	v_add_u32_e32 v20, vcc_hi, v4
	v_add_u32_e32 v21, vcc_hi, v5
	v_add_u32_e32 v22, vcc_hi, v6
	v_add_u32_e32 v23, vcc_hi, v7
	v_add_u32_e32 v24, vcc_hi, v8
	v_add_u32_e32 v25, vcc_hi, v9
	v_add_u32_e32 v26, vcc_hi, v10
	v_add_u32_e32 v27, vcc_hi, v11
	v_add_u32_e32 v28, vcc_hi, v12
	v_add_u32_e32 v29, vcc_hi, v13
	v_add_u32_e32 v30, vcc_hi, v14
	v_add_u32_e32 v31, vcc_hi, v15
	v_add_u32_e32 v32, vcc_hi, v16
	v_add_u32_e32 v33, vcc_hi, v17
	v_add_u32_e32 v34, vcc_hi, v18
	v_add_u32_e32 v35, vcc_hi, v19
	s_add_u32 vcc_lo, vcc_lo, 1
	s_barrier
	s_add_u32 m0, s100, 0x8000
	s_nop 0
	global_load_lds_dwordx4 v20, s[40:41]
	s_add_u32 m0, s100, 0x8400
	s_nop 0
	global_load_lds_dwordx4 v21, s[40:41]
	s_add_u32 m0, s100, 0x9000
	s_nop 0
	global_load_lds_dwordx4 v22, s[40:41]
	s_add_u32 m0, s100, 0x9400
	s_nop 0
	global_load_lds_dwordx4 v23, s[40:41]
	s_add_u32 m0, s100, 0xa000
	s_nop 0
	global_load_lds_dwordx4 v24, s[40:41]
	s_add_u32 m0, s100, 0xa400
	s_nop 0
	global_load_lds_dwordx4 v25, s[40:41]
	s_add_u32 m0, s100, 0xb000
	s_nop 0
	global_load_lds_dwordx4 v26, s[40:41]
	s_add_u32 m0, s100, 0xb400
	s_nop 0
	global_load_lds_dwordx4 v27, s[40:41]
	s_add_u32 m0, s100, 0xc000
	s_nop 0
	global_load_lds_dwordx4 v28, s[38:39]
	s_add_u32 m0, s100, 0xc400
	s_nop 0
	global_load_lds_dwordx4 v29, s[38:39]
	s_add_u32 m0, s100, 0xd000
	s_nop 0
	global_load_lds_dwordx4 v30, s[38:39]
	s_add_u32 m0, s100, 0xd400
	s_nop 0
	global_load_lds_dwordx4 v31, s[38:39]
	s_add_u32 m0, s100, 0xe000
	s_nop 0
	global_load_lds_dwordx4 v32, s[38:39]
	s_add_u32 m0, s100, 0xe400
	s_nop 0
	global_load_lds_dwordx4 v33, s[38:39]
	s_add_u32 m0, s100, 0xf000
	s_nop 0
	global_load_lds_dwordx4 v34, s[38:39]
	s_add_u32 m0, s100, 0xf400
	s_nop 0
	global_load_lds_dwordx4 v35, s[38:39]
	s_waitcnt vmcnt(16)
	s_barrier
	s_add_u32 s34, s34, 0x100
	s_addc_u32 s35, s35, 0
	s_add_i32 s55, s55, 2
	s_cmp_le_i32 s55, s47
	s_cbranch_scc1 .Lpc_ptop_4
	s_setprio 0
	s_mov_b32 s53, s49
	s_mov_b32 s52, s1
	v_mov_b64_e32 v[146:147], v[142:143]
	v_mov_b64_e32 v[144:145], v[140:141]
	s_and_b64 vcc, exec, s[26:27]
	s_cbranch_vccz .Lpc_pnd_4
	s_waitcnt vmcnt(0)
	s_branch .LBB0_342

.Lpc_pgo_1:
	s_nop 0
	s_sub_u32 s40, s40, s98
	s_subb_u32 s41, s41, 0
	s_sub_u32 s38, s38, s99
	s_subb_u32 s39, s39, 0
	s_bfe_u32 vcc_hi, s101, 0x80008
	s_add_u32 vcc_hi, vcc_hi, vcc_lo
	s_add_u32 m0, s42, -1
	s_and_b32 vcc_hi, vcc_hi, m0
	s_lshl_b32 vcc_hi, vcc_hi, 7
	v_add_u32_e32 v20, vcc_hi, v4
	v_add_u32_e32 v21, vcc_hi, v5
	v_add_u32_e32 v22, vcc_hi, v6
	v_add_u32_e32 v23, vcc_hi, v7
	v_add_u32_e32 v24, vcc_hi, v8
	v_add_u32_e32 v25, vcc_hi, v9
	v_add_u32_e32 v26, vcc_hi, v10
	v_add_u32_e32 v27, vcc_hi, v11
	v_add_u32_e32 v28, vcc_hi, v12
	v_add_u32_e32 v29, vcc_hi, v13
	v_add_u32_e32 v30, vcc_hi, v14
	v_add_u32_e32 v31, vcc_hi, v15
	v_add_u32_e32 v32, vcc_hi, v16
	v_add_u32_e32 v33, vcc_hi, v17
	v_add_u32_e32 v34, vcc_hi, v18
	v_add_u32_e32 v35, vcc_hi, v19
	s_add_u32 vcc_lo, vcc_lo, 1
	s_barrier
	s_add_u32 m0, s100, 0x0
	s_nop 0
	global_load_lds_dwordx4 v20, s[40:41]
	s_add_u32 m0, s100, 0x400
	s_nop 0
	global_load_lds_dwordx4 v21, s[40:41]
	s_add_u32 m0, s100, 0x1000
	s_nop 0
	global_load_lds_dwordx4 v22, s[40:41]
	s_add_u32 m0, s100, 0x1400
	s_nop 0
	global_load_lds_dwordx4 v23, s[40:41]
	s_add_u32 m0, s100, 0x2000
	s_nop 0
	global_load_lds_dwordx4 v24, s[40:41]
	s_add_u32 m0, s100, 0x2400
	s_nop 0
	global_load_lds_dwordx4 v25, s[40:41]
	s_add_u32 m0, s100, 0x3000
	s_nop 0
	global_load_lds_dwordx4 v26, s[40:41]
	s_add_u32 m0, s100, 0x3400
	s_nop 0
	global_load_lds_dwordx4 v27, s[40:41]
	s_add_u32 m0, s100, 0x4000
	s_nop 0
	global_load_lds_dwordx4 v28, s[38:39]
	s_add_u32 m0, s100, 0x4400
	s_nop 0
	global_load_lds_dwordx4 v29, s[38:39]
	s_add_u32 m0, s100, 0x5000
	s_nop 0
	global_load_lds_dwordx4 v30, s[38:39]
	s_add_u32 m0, s100, 0x5400
	s_nop 0
	global_load_lds_dwordx4 v31, s[38:39]
	s_add_u32 m0, s100, 0x6000
	s_nop 0
	global_load_lds_dwordx4 v32, s[38:39]
	s_add_u32 m0, s100, 0x6400
	s_nop 0
	global_load_lds_dwordx4 v33, s[38:39]
	s_add_u32 m0, s100, 0x7000
	s_nop 0
	global_load_lds_dwordx4 v34, s[38:39]
	s_add_u32 m0, s100, 0x7400
	s_nop 0
	global_load_lds_dwordx4 v35, s[38:39]
	s_waitcnt vmcnt(16)
	s_barrier
	s_bfe_u32 vcc_hi, s101, 0x80008
	s_add_u32 vcc_hi, vcc_hi, vcc_lo
	s_add_u32 m0, s42, -1
	s_and_b32 vcc_hi, vcc_hi, m0
	s_lshl_b32 vcc_hi, vcc_hi, 7
	v_add_u32_e32 v20, vcc_hi, v4
	v_add_u32_e32 v21, vcc_hi, v5
	v_add_u32_e32 v22, vcc_hi, v6
	v_add_u32_e32 v23, vcc_hi, v7
	v_add_u32_e32 v24, vcc_hi, v8
	v_add_u32_e32 v25, vcc_hi, v9
	v_add_u32_e32 v26, vcc_hi, v10
	v_add_u32_e32 v27, vcc_hi, v11
	v_add_u32_e32 v28, vcc_hi, v12
	v_add_u32_e32 v29, vcc_hi, v13
	v_add_u32_e32 v30, vcc_hi, v14
	v_add_u32_e32 v31, vcc_hi, v15
	v_add_u32_e32 v32, vcc_hi, v16
	v_add_u32_e32 v33, vcc_hi, v17
	v_add_u32_e32 v34, vcc_hi, v18
	v_add_u32_e32 v35, vcc_hi, v19
	s_add_u32 vcc_lo, vcc_lo, 1
	s_barrier
	s_add_u32 m0, s100, 0x8000
	s_nop 0
	global_load_lds_dwordx4 v20, s[40:41]
	s_add_u32 m0, s100, 0x8400
	s_nop 0
	global_load_lds_dwordx4 v21, s[40:41]
	s_add_u32 m0, s100, 0x9000
	s_nop 0
	global_load_lds_dwordx4 v22, s[40:41]
	s_add_u32 m0, s100, 0x9400
	s_nop 0
	global_load_lds_dwordx4 v23, s[40:41]
	s_add_u32 m0, s100, 0xa000
	s_nop 0
	global_load_lds_dwordx4 v24, s[40:41]
	s_add_u32 m0, s100, 0xa400
	s_nop 0
	global_load_lds_dwordx4 v25, s[40:41]
	s_add_u32 m0, s100, 0xb000
	s_nop 0
	global_load_lds_dwordx4 v26, s[40:41]
	s_add_u32 m0, s100, 0xb400
	s_nop 0
	global_load_lds_dwordx4 v27, s[40:41]
	s_add_u32 m0, s100, 0xc000
	s_nop 0
	global_load_lds_dwordx4 v28, s[38:39]
	s_add_u32 m0, s100, 0xc400
	s_nop 0
	global_load_lds_dwordx4 v29, s[38:39]
	s_add_u32 m0, s100, 0xd000
	s_nop 0
	global_load_lds_dwordx4 v30, s[38:39]
	s_add_u32 m0, s100, 0xd400
	s_nop 0
	global_load_lds_dwordx4 v31, s[38:39]
	s_add_u32 m0, s100, 0xe000
	s_nop 0
	global_load_lds_dwordx4 v32, s[38:39]
	s_add_u32 m0, s100, 0xe400
	s_nop 0
	global_load_lds_dwordx4 v33, s[38:39]
	s_add_u32 m0, s100, 0xf000
	s_nop 0
	global_load_lds_dwordx4 v34, s[38:39]
	s_add_u32 m0, s100, 0xf400
	s_nop 0
	global_load_lds_dwordx4 v35, s[38:39]
	s_waitcnt vmcnt(16)
	s_barrier
	s_add_u32 s34, s34, 0x100
	s_addc_u32 s35, s35, 0
	s_add_i32 s53, s53, 2
	s_cmp_le_i32 s53, s47
	s_cbranch_scc1 .Lpc_ptop_1
	s_setprio 0
	s_movk_i32 s4, 0x3100
	s_mov_b32 s52, s48
	s_mov_b32 s49, s1
	s_and_b64 vcc, exec, s[26:27]
	v_mov_b64_e32 v[146:147], v[142:143]
	v_mov_b64_e32 v[144:145], v[140:141]
	s_cbranch_vccz .Lpc_pnd_1
	s_waitcnt vmcnt(0)
	s_branch .LBB0_965
